# out-projection fused epilogue: the 32 row sum-of-squares cross-lane reductions via v_permlane16/32_swap instead of ds_bpermute
# speedup vs baseline: 1.0185x; 1.0027x over previous
;     __device__ __forceinline__ void fused(f32x4 (&acc)[2][2][4][2], const pg8::Unit& u, int wr, int wc, int fr, int fq, LAS unsigned char* lds, int wid, int lane) const {
;     ...
; #pragma unroll
;         for (int ai = 0; ai < 2; ++ai)
; #pragma unroll
;             for (int m = 0; m < 4; ++m) {
;                 const int rl = ai * 128 + wr * 64 + m * 16 + fr; const int row = u.pm * 256 + rl;
;                 const float s = ssq_in ? rsqrtf((S0[rl] + S0[256 + rl]) * inv_k + EPS_) : 1.0f; (void)row;
;                 float q = 0.f;
; #pragma unroll
;                 for (int bj = 0; bj < 2; ++bj)
; #pragma unroll
;                     for (int n = 0; n < 2; ++n) { f32x4 v = acc[ai][bj][m][n] * s; acc[ai][bj][m][n] = v; q += (v[0] * v[0] + v[1] * v[1]) + (v[2] * v[2] + v[3] * v[3]); }
;                 q += __shfl_xor(q, 16); q += __shfl_xor(q, 32);
;                 if (fq == 0) P[rl * 4 + wc] = q;
.LBB0_554:
	v_cmp_lt_i32_e32 vcc, v213, v208
	v_pk_mul_f32 v[196:197], v[136:137], v[2:3] op_sel_hi:[1,0]
	v_pk_mul_f32 v[198:199], v[134:135], v[2:3] op_sel_hi:[1,0]
	v_cndmask_b32_e32 v5, v207, v213, vcc
	v_pk_mul_f32 v[200:201], v[132:133], v[2:3] op_sel_hi:[1,0]
	v_pk_mul_f32 v[202:203], v[130:131], v[2:3] op_sel_hi:[1,0]
	v_lshlrev_b32_e32 v222, 2, v5
	v_mul_f32_e32 v5, v199, v199
	v_mul_f32_e32 v134, v197, v197
	v_mul_f32_e32 v130, v203, v203
	v_mul_f32_e32 v131, v201, v201
	v_pk_mul_f32 v[188:189], v[128:129], v[2:3] op_sel_hi:[1,0]
	v_pk_mul_f32 v[192:193], v[126:127], v[2:3] op_sel_hi:[1,0]
	v_fmac_f32_e32 v5, v198, v198
	v_fmac_f32_e32 v134, v196, v196
	v_fmac_f32_e32 v130, v202, v202
	v_fmac_f32_e32 v131, v200, v200
	v_mul_f32_e32 v126, v193, v193
	v_mul_f32_e32 v127, v189, v189
	v_pk_mul_f32 v[190:191], v[124:125], v[2:3] op_sel_hi:[1,0]
	v_pk_mul_f32 v[194:195], v[122:123], v[2:3] op_sel_hi:[1,0]
	v_add_f32_e32 v5, v5, v134
	v_add_f32_e32 v130, v130, v131
	v_fmac_f32_e32 v126, v192, v192
	v_fmac_f32_e32 v127, v188, v188
	v_mul_f32_e32 v2, v195, v195
	v_mul_f32_e32 v122, v191, v191
	v_add_f32_e32 v5, v5, v130
	v_add_f32_e32 v126, v126, v127
	v_fmac_f32_e32 v2, v194, v194
	v_fmac_f32_e32 v122, v190, v190
	v_add_f32_e32 v5, v126, v5
	v_add_f32_e32 v2, v2, v122
	v_add_f32_e32 v2, v2, v5
	v_mov_b32_e32 v5, v2
	v_cmp_lt_i32_e32 vcc, v214, v208
	s_lshl_b32 s0, s36, 2
	v_and_b32_e32 v240, 63, v220
	v_cndmask_b32_e32 v122, v207, v214, vcc
	v_lshlrev_b32_e32 v223, 2, v122
	s_waitcnt lgkmcnt(0)
	v_permlane16_swap_b32 v5, v2
	v_add_f32_e32 v2, v2, v5
	v_mov_b32_e32 v5, v2
	s_add_i32 s2, s0, 0
	v_cmp_gt_u32_e64 s[4:5], 16, v240
	v_lshl_add_u32 v238, v221, 4, s2
	v_permlane32_swap_b32 v5, v2
	s_and_saveexec_b64 s[0:1], s[4:5]
	s_cbranch_execz .LBB0_556
	s_waitcnt lgkmcnt(0)
	v_add_f32_e32 v2, v2, v5
	ds_write_b32 v238, v2

;     __device__ __forceinline__ void fused(f32x4 (&acc)[2][2][4][2], const pg8::Unit& u, int wr, int wc, int fr, int fq, LAS unsigned char* lds, int wid, int lane) const {
;     ...
; #pragma unroll
;         for (int ai = 0; ai < 2; ++ai)
; #pragma unroll
;             for (int m = 0; m < 4; ++m) {
;                 const int rl = ai * 128 + wr * 64 + m * 16 + fr; const int row = u.pm * 256 + rl;
;                 const float s = ssq_in ? rsqrtf((S0[rl] + S0[256 + rl]) * inv_k + EPS_) : 1.0f; (void)row;
;                 float q = 0.f;
; #pragma unroll
;                 for (int bj = 0; bj < 2; ++bj)
; #pragma unroll
;                     for (int n = 0; n < 2; ++n) { f32x4 v = acc[ai][bj][m][n] * s; acc[ai][bj][m][n] = v; q += (v[0] * v[0] + v[1] * v[1]) + (v[2] * v[2] + v[3] * v[3]); }
;                 q += __shfl_xor(q, 16); q += __shfl_xor(q, 32);
;                 if (fq == 0) P[rl * 4 + wc] = q;
.LBB0_559:
	v_pk_mul_f32 v[180:181], v[120:121], v[2:3] op_sel_hi:[1,0]
	v_pk_mul_f32 v[184:185], v[118:119], v[2:3] op_sel_hi:[1,0]
	v_pk_mul_f32 v[182:183], v[116:117], v[2:3] op_sel_hi:[1,0]
	v_pk_mul_f32 v[186:187], v[114:115], v[2:3] op_sel_hi:[1,0]
	s_waitcnt lgkmcnt(0)
	v_mul_f32_e32 v5, v185, v185
	v_mul_f32_e32 v118, v181, v181
	v_mul_f32_e32 v114, v187, v187
	v_mul_f32_e32 v115, v183, v183
	v_pk_mul_f32 v[166:167], v[112:113], v[2:3] op_sel_hi:[1,0]
	v_pk_mul_f32 v[176:177], v[110:111], v[2:3] op_sel_hi:[1,0]
	v_fmac_f32_e32 v5, v184, v184
	v_fmac_f32_e32 v118, v180, v180
	v_fmac_f32_e32 v114, v186, v186
	v_fmac_f32_e32 v115, v182, v182
	v_mul_f32_e32 v110, v177, v177
	v_mul_f32_e32 v111, v167, v167
	v_pk_mul_f32 v[168:169], v[108:109], v[2:3] op_sel_hi:[1,0]
	v_pk_mul_f32 v[178:179], v[106:107], v[2:3] op_sel_hi:[1,0]
	v_add_f32_e32 v5, v5, v118
	v_add_f32_e32 v114, v114, v115
	v_fmac_f32_e32 v110, v176, v176
	v_fmac_f32_e32 v111, v166, v166
	v_mul_f32_e32 v2, v179, v179
	v_mul_f32_e32 v106, v169, v169
	v_add_f32_e32 v5, v5, v114
	v_add_f32_e32 v110, v110, v111
	v_fmac_f32_e32 v2, v178, v178
	v_fmac_f32_e32 v106, v168, v168
	v_add_f32_e32 v5, v110, v5
	v_add_f32_e32 v2, v2, v106
	v_add_f32_e32 v2, v2, v5
	v_mov_b32_e32 v5, v2
	v_or_b32_e32 v239, 16, v221
	v_lshl_add_u32 v236, v239, 4, s2
	s_waitcnt lgkmcnt(0)
	v_permlane16_swap_b32 v5, v2
	v_add_f32_e32 v2, v2, v5
	v_mov_b32_e32 v5, v2
	s_nop 1
	v_permlane32_swap_b32 v5, v2
	s_and_saveexec_b64 s[0:1], s[4:5]
	s_cbranch_execz .LBB0_561
	s_waitcnt lgkmcnt(0)
	v_add_f32_e32 v2, v2, v5
	ds_write_b32 v236, v2

;     __device__ __forceinline__ void fused(f32x4 (&acc)[2][2][4][2], const pg8::Unit& u, int wr, int wc, int fr, int fq, LAS unsigned char* lds, int wid, int lane) const {
;     ...
; #pragma unroll
;         for (int ai = 0; ai < 2; ++ai)
; #pragma unroll
;             for (int m = 0; m < 4; ++m) {
;                 const int rl = ai * 128 + wr * 64 + m * 16 + fr; const int row = u.pm * 256 + rl;
;                 const float s = ssq_in ? rsqrtf((S0[rl] + S0[256 + rl]) * inv_k + EPS_) : 1.0f; (void)row;
;                 float q = 0.f;
; #pragma unroll
;                 for (int bj = 0; bj < 2; ++bj)
; #pragma unroll
;                     for (int n = 0; n < 2; ++n) { f32x4 v = acc[ai][bj][m][n] * s; acc[ai][bj][m][n] = v; q += (v[0] * v[0] + v[1] * v[1]) + (v[2] * v[2] + v[3] * v[3]); }
;                 q += __shfl_xor(q, 16); q += __shfl_xor(q, 32);
;                 if (fq == 0) P[rl * 4 + wc] = q;
.LBB0_564:
	v_pk_mul_f32 v[158:159], v[104:105], v[2:3] op_sel_hi:[1,0]
	v_pk_mul_f32 v[162:163], v[102:103], v[2:3] op_sel_hi:[1,0]
	v_pk_mul_f32 v[160:161], v[100:101], v[2:3] op_sel_hi:[1,0]
	v_pk_mul_f32 v[164:165], v[98:99], v[2:3] op_sel_hi:[1,0]
	s_waitcnt lgkmcnt(0)
	v_mul_f32_e32 v5, v163, v163
	v_mul_f32_e32 v102, v159, v159
	v_mul_f32_e32 v98, v165, v165
	v_mul_f32_e32 v99, v161, v161
	v_pk_mul_f32 v[150:151], v[96:97], v[2:3] op_sel_hi:[1,0]
	v_pk_mul_f32 v[154:155], v[94:95], v[2:3] op_sel_hi:[1,0]
	v_fmac_f32_e32 v5, v162, v162
	v_fmac_f32_e32 v102, v158, v158
	v_fmac_f32_e32 v98, v164, v164
	v_fmac_f32_e32 v99, v160, v160
	v_mul_f32_e32 v94, v155, v155
	v_mul_f32_e32 v95, v151, v151
	v_pk_mul_f32 v[152:153], v[92:93], v[2:3] op_sel_hi:[1,0]
	v_pk_mul_f32 v[156:157], v[90:91], v[2:3] op_sel_hi:[1,0]
	v_add_f32_e32 v5, v5, v102
	v_add_f32_e32 v98, v98, v99
	v_fmac_f32_e32 v94, v154, v154
	v_fmac_f32_e32 v95, v150, v150
	v_mul_f32_e32 v2, v157, v157
	v_mul_f32_e32 v90, v153, v153
	v_add_f32_e32 v5, v5, v98
	v_add_f32_e32 v94, v94, v95
	v_fmac_f32_e32 v2, v156, v156
	v_fmac_f32_e32 v90, v152, v152
	v_add_f32_e32 v5, v94, v5
	v_add_f32_e32 v2, v2, v90
	v_add_f32_e32 v2, v2, v5
	v_mov_b32_e32 v5, v2
	v_or_b32_e32 v237, 32, v221
	v_lshl_add_u32 v234, v237, 4, s2
	s_waitcnt lgkmcnt(0)
	v_permlane16_swap_b32 v5, v2
	v_add_f32_e32 v2, v2, v5
	v_mov_b32_e32 v5, v2
	s_nop 1
	v_permlane32_swap_b32 v5, v2
	s_and_saveexec_b64 s[0:1], s[4:5]
	s_cbranch_execz .LBB0_566
	s_waitcnt lgkmcnt(0)
	v_add_f32_e32 v2, v2, v5
	ds_write_b32 v234, v2

;     __device__ __forceinline__ void fused(f32x4 (&acc)[2][2][4][2], const pg8::Unit& u, int wr, int wc, int fr, int fq, LAS unsigned char* lds, int wid, int lane) const {
;     ...
; #pragma unroll
;         for (int ai = 0; ai < 2; ++ai)
; #pragma unroll
;             for (int m = 0; m < 4; ++m) {
;                 const int rl = ai * 128 + wr * 64 + m * 16 + fr; const int row = u.pm * 256 + rl;
;                 const float s = ssq_in ? rsqrtf((S0[rl] + S0[256 + rl]) * inv_k + EPS_) : 1.0f; (void)row;
;                 float q = 0.f;
; #pragma unroll
;                 for (int bj = 0; bj < 2; ++bj)
; #pragma unroll
;                     for (int n = 0; n < 2; ++n) { f32x4 v = acc[ai][bj][m][n] * s; acc[ai][bj][m][n] = v; q += (v[0] * v[0] + v[1] * v[1]) + (v[2] * v[2] + v[3] * v[3]); }
;                 q += __shfl_xor(q, 16); q += __shfl_xor(q, 32);
;                 if (fq == 0) P[rl * 4 + wc] = q;
.LBB0_569:
	v_pk_mul_f32 v[142:143], v[88:89], v[2:3] op_sel_hi:[1,0]
	v_pk_mul_f32 v[146:147], v[86:87], v[2:3] op_sel_hi:[1,0]
	v_pk_mul_f32 v[144:145], v[84:85], v[2:3] op_sel_hi:[1,0]
	v_pk_mul_f32 v[148:149], v[82:83], v[2:3] op_sel_hi:[1,0]
	s_waitcnt lgkmcnt(0)
	v_mul_f32_e32 v5, v147, v147
	v_mul_f32_e32 v86, v143, v143
	v_mul_f32_e32 v82, v149, v149
	v_mul_f32_e32 v83, v145, v145
	v_pk_mul_f32 v[134:135], v[80:81], v[2:3] op_sel_hi:[1,0]
	v_pk_mul_f32 v[138:139], v[78:79], v[2:3] op_sel_hi:[1,0]
	v_fmac_f32_e32 v5, v146, v146
	v_fmac_f32_e32 v86, v142, v142
	v_fmac_f32_e32 v82, v148, v148
	v_fmac_f32_e32 v83, v144, v144
	v_mul_f32_e32 v78, v139, v139
	v_mul_f32_e32 v79, v135, v135
	v_pk_mul_f32 v[136:137], v[76:77], v[2:3] op_sel_hi:[1,0]
	v_pk_mul_f32 v[140:141], v[74:75], v[2:3] op_sel_hi:[1,0]
	v_add_f32_e32 v5, v5, v86
	v_add_f32_e32 v82, v82, v83
	v_fmac_f32_e32 v78, v138, v138
	v_fmac_f32_e32 v79, v134, v134
	v_mul_f32_e32 v2, v141, v141
	v_mul_f32_e32 v74, v137, v137
	v_add_f32_e32 v5, v5, v82
	v_add_f32_e32 v78, v78, v79
	v_fmac_f32_e32 v2, v140, v140
	v_fmac_f32_e32 v74, v136, v136
	v_add_f32_e32 v5, v78, v5
	v_add_f32_e32 v2, v2, v74
	v_add_f32_e32 v2, v2, v5
	v_mov_b32_e32 v5, v2
	v_or_b32_e32 v235, 48, v221
	v_lshl_add_u32 v232, v235, 4, s2
	s_waitcnt lgkmcnt(0)
	v_permlane16_swap_b32 v5, v2
	v_add_f32_e32 v2, v2, v5
	v_mov_b32_e32 v5, v2
	s_nop 1
	v_permlane32_swap_b32 v5, v2
	s_and_saveexec_b64 s[0:1], s[4:5]
	s_cbranch_execz .LBB0_571
	s_waitcnt lgkmcnt(0)
	v_add_f32_e32 v2, v2, v5
	ds_write_b32 v232, v2

;     __device__ __forceinline__ void fused(f32x4 (&acc)[2][2][4][2], const pg8::Unit& u, int wr, int wc, int fr, int fq, LAS unsigned char* lds, int wid, int lane) const {
;     ...
; #pragma unroll
;         for (int ai = 0; ai < 2; ++ai)
; #pragma unroll
;             for (int m = 0; m < 4; ++m) {
;                 const int rl = ai * 128 + wr * 64 + m * 16 + fr; const int row = u.pm * 256 + rl;
;                 const float s = ssq_in ? rsqrtf((S0[rl] + S0[256 + rl]) * inv_k + EPS_) : 1.0f; (void)row;
;                 float q = 0.f;
; #pragma unroll
;                 for (int bj = 0; bj < 2; ++bj)
; #pragma unroll
;                     for (int n = 0; n < 2; ++n) { f32x4 v = acc[ai][bj][m][n] * s; acc[ai][bj][m][n] = v; q += (v[0] * v[0] + v[1] * v[1]) + (v[2] * v[2] + v[3] * v[3]); }
;                 q += __shfl_xor(q, 16); q += __shfl_xor(q, 32);
;                 if (fq == 0) P[rl * 4 + wc] = q;
.LBB0_574:
	v_pk_mul_f32 v[126:127], v[72:73], v[2:3] op_sel_hi:[1,0]
	v_pk_mul_f32 v[128:129], v[70:71], v[2:3] op_sel_hi:[1,0]
	v_pk_mul_f32 v[130:131], v[68:69], v[2:3] op_sel_hi:[1,0]
	v_pk_mul_f32 v[132:133], v[66:67], v[2:3] op_sel_hi:[1,0]
	s_waitcnt lgkmcnt(0)
	v_mul_f32_e32 v5, v129, v129
	v_mul_f32_e32 v70, v127, v127
	v_mul_f32_e32 v66, v133, v133
	v_mul_f32_e32 v67, v131, v131
	v_pk_mul_f32 v[118:119], v[64:65], v[2:3] op_sel_hi:[1,0]
	v_pk_mul_f32 v[122:123], v[62:63], v[2:3] op_sel_hi:[1,0]
	v_fmac_f32_e32 v5, v128, v128
	v_fmac_f32_e32 v70, v126, v126
	v_fmac_f32_e32 v66, v132, v132
	v_fmac_f32_e32 v67, v130, v130
	v_mul_f32_e32 v62, v123, v123
	v_mul_f32_e32 v63, v119, v119
	v_pk_mul_f32 v[120:121], v[60:61], v[2:3] op_sel_hi:[1,0]
	v_pk_mul_f32 v[124:125], v[58:59], v[2:3] op_sel_hi:[1,0]
	v_add_f32_e32 v5, v5, v70
	v_add_f32_e32 v66, v66, v67
	v_fmac_f32_e32 v62, v122, v122
	v_fmac_f32_e32 v63, v118, v118
	v_mul_f32_e32 v2, v125, v125
	v_mul_f32_e32 v58, v121, v121
	v_add_f32_e32 v5, v5, v66
	v_add_f32_e32 v62, v62, v63
	v_fmac_f32_e32 v2, v124, v124
	v_fmac_f32_e32 v58, v120, v120
	v_add_f32_e32 v5, v62, v5
	v_add_f32_e32 v2, v2, v58
	v_add_f32_e32 v2, v2, v5
	v_mov_b32_e32 v5, v2
	v_add_u32_e32 v233, 0x80, v221
	v_lshl_add_u32 v230, v233, 4, s2
	s_waitcnt lgkmcnt(0)
	v_permlane16_swap_b32 v5, v2
	v_add_f32_e32 v2, v2, v5
	v_mov_b32_e32 v5, v2
	s_nop 1
	v_permlane32_swap_b32 v5, v2
	s_and_saveexec_b64 s[0:1], s[4:5]
	s_cbranch_execz .LBB0_576
	s_waitcnt lgkmcnt(0)
	v_add_f32_e32 v2, v2, v5
	ds_write_b32 v230, v2

;     __device__ __forceinline__ void fused(f32x4 (&acc)[2][2][4][2], const pg8::Unit& u, int wr, int wc, int fr, int fq, LAS unsigned char* lds, int wid, int lane) const {
;     ...
; #pragma unroll
;         for (int ai = 0; ai < 2; ++ai)
; #pragma unroll
;             for (int m = 0; m < 4; ++m) {
;                 const int rl = ai * 128 + wr * 64 + m * 16 + fr; const int row = u.pm * 256 + rl;
;                 const float s = ssq_in ? rsqrtf((S0[rl] + S0[256 + rl]) * inv_k + EPS_) : 1.0f; (void)row;
;                 float q = 0.f;
; #pragma unroll
;                 for (int bj = 0; bj < 2; ++bj)
; #pragma unroll
;                     for (int n = 0; n < 2; ++n) { f32x4 v = acc[ai][bj][m][n] * s; acc[ai][bj][m][n] = v; q += (v[0] * v[0] + v[1] * v[1]) + (v[2] * v[2] + v[3] * v[3]); }
;                 q += __shfl_xor(q, 16); q += __shfl_xor(q, 32);
;                 if (fq == 0) P[rl * 4 + wc] = q;
.LBB0_579:
	v_pk_mul_f32 v[110:111], v[56:57], v[2:3] op_sel_hi:[1,0]
	v_pk_mul_f32 v[114:115], v[54:55], v[2:3] op_sel_hi:[1,0]
	v_pk_mul_f32 v[112:113], v[52:53], v[2:3] op_sel_hi:[1,0]
	v_pk_mul_f32 v[116:117], v[50:51], v[2:3] op_sel_hi:[1,0]
	s_waitcnt lgkmcnt(0)
	v_mul_f32_e32 v5, v115, v115
	v_mul_f32_e32 v54, v111, v111
	v_mul_f32_e32 v50, v117, v117
	v_mul_f32_e32 v51, v113, v113
	v_pk_mul_f32 v[100:101], v[48:49], v[2:3] op_sel_hi:[1,0]
	v_pk_mul_f32 v[106:107], v[46:47], v[2:3] op_sel_hi:[1,0]
	v_fmac_f32_e32 v5, v114, v114
	v_fmac_f32_e32 v54, v110, v110
	v_fmac_f32_e32 v50, v116, v116
	v_fmac_f32_e32 v51, v112, v112
	v_mul_f32_e32 v46, v107, v107
	v_mul_f32_e32 v47, v101, v101
	v_pk_mul_f32 v[104:105], v[44:45], v[2:3] op_sel_hi:[1,0]
	v_pk_mul_f32 v[108:109], v[42:43], v[2:3] op_sel_hi:[1,0]
	v_add_f32_e32 v5, v5, v54
	v_add_f32_e32 v50, v50, v51
	v_fmac_f32_e32 v46, v106, v106
	v_fmac_f32_e32 v47, v100, v100
	v_mul_f32_e32 v2, v109, v109
	v_mul_f32_e32 v42, v105, v105
	v_add_f32_e32 v5, v5, v50
	v_add_f32_e32 v46, v46, v47
	v_fmac_f32_e32 v2, v108, v108
	v_fmac_f32_e32 v42, v104, v104
	v_add_f32_e32 v5, v46, v5
	v_add_f32_e32 v2, v2, v42
	v_add_f32_e32 v2, v2, v5
	v_mov_b32_e32 v5, v2
	v_add_u32_e32 v231, 0x90, v221
	v_lshl_add_u32 v228, v231, 4, s2
	s_waitcnt lgkmcnt(0)
	v_permlane16_swap_b32 v5, v2
	v_add_f32_e32 v2, v2, v5
	v_mov_b32_e32 v5, v2
	s_nop 1
	v_permlane32_swap_b32 v5, v2
	s_and_saveexec_b64 s[0:1], s[4:5]
	s_cbranch_execz .LBB0_581
	s_waitcnt lgkmcnt(0)
	v_add_f32_e32 v2, v2, v5
	ds_write_b32 v228, v2

;     __device__ __forceinline__ void fused(f32x4 (&acc)[2][2][4][2], const pg8::Unit& u, int wr, int wc, int fr, int fq, LAS unsigned char* lds, int wid, int lane) const {
;     ...
; #pragma unroll
;         for (int ai = 0; ai < 2; ++ai)
; #pragma unroll
;             for (int m = 0; m < 4; ++m) {
;                 const int rl = ai * 128 + wr * 64 + m * 16 + fr; const int row = u.pm * 256 + rl;
;                 const float s = ssq_in ? rsqrtf((S0[rl] + S0[256 + rl]) * inv_k + EPS_) : 1.0f; (void)row;
;                 float q = 0.f;
; #pragma unroll
;                 for (int bj = 0; bj < 2; ++bj)
; #pragma unroll
;                     for (int n = 0; n < 2; ++n) { f32x4 v = acc[ai][bj][m][n] * s; acc[ai][bj][m][n] = v; q += (v[0] * v[0] + v[1] * v[1]) + (v[2] * v[2] + v[3] * v[3]); }
;                 q += __shfl_xor(q, 16); q += __shfl_xor(q, 32);
;                 if (fq == 0) P[rl * 4 + wc] = q;
.LBB0_584:
	v_pk_mul_f32 v[90:91], v[40:41], v[2:3] op_sel_hi:[1,0]
	v_pk_mul_f32 v[94:95], v[38:39], v[2:3] op_sel_hi:[1,0]
	v_pk_mul_f32 v[92:93], v[36:37], v[2:3] op_sel_hi:[1,0]
	v_pk_mul_f32 v[96:97], v[34:35], v[2:3] op_sel_hi:[1,0]
	s_waitcnt lgkmcnt(0)
	v_mul_f32_e32 v5, v95, v95
	v_mul_f32_e32 v38, v91, v91
	v_mul_f32_e32 v34, v97, v97
	v_mul_f32_e32 v35, v93, v93
	v_pk_mul_f32 v[82:83], v[32:33], v[2:3] op_sel_hi:[1,0]
	v_pk_mul_f32 v[86:87], v[30:31], v[2:3] op_sel_hi:[1,0]
	v_fmac_f32_e32 v5, v94, v94
	v_fmac_f32_e32 v38, v90, v90
	v_fmac_f32_e32 v34, v96, v96
	v_fmac_f32_e32 v35, v92, v92
	v_mul_f32_e32 v30, v87, v87
	v_mul_f32_e32 v31, v83, v83
	v_pk_mul_f32 v[84:85], v[28:29], v[2:3] op_sel_hi:[1,0]
	v_pk_mul_f32 v[88:89], v[26:27], v[2:3] op_sel_hi:[1,0]
	v_add_f32_e32 v5, v5, v38
	v_add_f32_e32 v34, v34, v35
	v_fmac_f32_e32 v30, v86, v86
	v_fmac_f32_e32 v31, v82, v82
	v_mul_f32_e32 v2, v89, v89
	v_mul_f32_e32 v26, v85, v85
	v_add_f32_e32 v5, v5, v34
	v_add_f32_e32 v30, v30, v31
	v_fmac_f32_e32 v2, v88, v88
	v_fmac_f32_e32 v26, v84, v84
	v_add_f32_e32 v5, v30, v5
	v_add_f32_e32 v2, v2, v26
	v_add_f32_e32 v2, v2, v5
	v_mov_b32_e32 v5, v2
	v_add_u32_e32 v229, 0xa0, v221
	v_lshl_add_u32 v226, v229, 4, s2
	s_waitcnt lgkmcnt(0)
	v_permlane16_swap_b32 v5, v2
	v_add_f32_e32 v2, v2, v5
	v_mov_b32_e32 v5, v2
	s_nop 1
	v_permlane32_swap_b32 v5, v2
	s_and_saveexec_b64 s[0:1], s[4:5]
	s_cbranch_execz .LBB0_586
	s_waitcnt lgkmcnt(0)
	v_add_f32_e32 v2, v2, v5
	ds_write_b32 v226, v2

;     __device__ __forceinline__ void fused(f32x4 (&acc)[2][2][4][2], const pg8::Unit& u, int wr, int wc, int fr, int fq, LAS unsigned char* lds, int wid, int lane) const {
;     ...
; #pragma unroll
;         for (int ai = 0; ai < 2; ++ai)
; #pragma unroll
;             for (int m = 0; m < 4; ++m) {
;                 const int rl = ai * 128 + wr * 64 + m * 16 + fr; const int row = u.pm * 256 + rl;
;                 const float s = ssq_in ? rsqrtf((S0[rl] + S0[256 + rl]) * inv_k + EPS_) : 1.0f; (void)row;
;                 float q = 0.f;
; #pragma unroll
;                 for (int bj = 0; bj < 2; ++bj)
; #pragma unroll
;                     for (int n = 0; n < 2; ++n) { f32x4 v = acc[ai][bj][m][n] * s; acc[ai][bj][m][n] = v; q += (v[0] * v[0] + v[1] * v[1]) + (v[2] * v[2] + v[3] * v[3]); }
;                 q += __shfl_xor(q, 16); q += __shfl_xor(q, 32);
;                 if (fq == 0) P[rl * 4 + wc] = q;
.LBB0_589:
	v_pk_mul_f32 v[74:75], v[24:25], v[2:3] op_sel_hi:[1,0]
	v_pk_mul_f32 v[78:79], v[22:23], v[2:3] op_sel_hi:[1,0]
	v_pk_mul_f32 v[76:77], v[20:21], v[2:3] op_sel_hi:[1,0]
	v_pk_mul_f32 v[80:81], v[18:19], v[2:3] op_sel_hi:[1,0]
	s_waitcnt lgkmcnt(0)
	v_mul_f32_e32 v5, v79, v79
	v_mul_f32_e32 v22, v75, v75
	v_mul_f32_e32 v18, v81, v81
	v_mul_f32_e32 v19, v77, v77
	v_pk_mul_f32 v[66:67], v[16:17], v[2:3] op_sel_hi:[1,0]
	v_pk_mul_f32 v[70:71], v[14:15], v[2:3] op_sel_hi:[1,0]
	v_fmac_f32_e32 v5, v78, v78
	v_fmac_f32_e32 v22, v74, v74
	v_fmac_f32_e32 v18, v80, v80
	v_fmac_f32_e32 v19, v76, v76
	v_mul_f32_e32 v14, v71, v71
	v_mul_f32_e32 v15, v67, v67
	v_pk_mul_f32 v[68:69], v[12:13], v[2:3] op_sel_hi:[1,0]
	v_pk_mul_f32 v[72:73], v[10:11], v[2:3] op_sel_hi:[1,0]
	v_add_f32_e32 v5, v5, v22
	v_add_f32_e32 v18, v18, v19
	v_fmac_f32_e32 v14, v70, v70
	v_fmac_f32_e32 v15, v66, v66
	v_mul_f32_e32 v2, v73, v73
	v_mul_f32_e32 v10, v69, v69
	v_add_f32_e32 v5, v5, v18
	v_add_f32_e32 v14, v14, v15
	v_fmac_f32_e32 v2, v72, v72
	v_fmac_f32_e32 v10, v68, v68
	v_add_f32_e32 v5, v14, v5
	v_add_f32_e32 v2, v2, v10
	v_add_f32_e32 v2, v2, v5
	v_mov_b32_e32 v5, v2
	v_readlane_b32 s22, v255, 16
	v_add_u32_e32 v227, 0xb0, v221
	v_readlane_b32 s23, v255, 17
	v_readlane_b32 s68, v255, 29
	s_waitcnt lgkmcnt(0)
	v_permlane16_swap_b32 v5, v2
	v_add_f32_e32 v5, v2, v5
	v_mov_b32_e32 v10, v5
	v_lshl_add_u32 v2, v227, 4, s2
	v_readlane_b32 s69, v255, 30
	v_permlane32_swap_b32 v10, v5
	s_and_saveexec_b64 s[0:1], s[4:5]
	s_cbranch_execz .LBB0_591
	s_waitcnt lgkmcnt(0)
	v_add_f32_e32 v5, v5, v10
	ds_write_b32 v2, v5

; __device__ __forceinline__ uint4 pack8(const float* f) { uint4 o; o.x = pk2(f[0], f[1]); o.y = pk2(f[2], f[3]); o.z = pk2(f[4], f[5]); o.w = pk2(f[6], f[7]); return o; }
;     __device__ __forceinline__ void fused(f32x4 (&acc)[2][2][4][2], const pg8::Unit& u, int wr, int wc, int fr, int fq, LAS unsigned char* lds, int wid, int lane) const {
;     ...
;             for (int m = 0; m < 4; ++m) {
;                 const int rl = ai * 128 + wr * 64 + m * 16 + fr; const size_t off = (size_t)(u.pm * 256 + rl) * 1024 + cb;
;                 const float rsf = S[rl]; float q = 0.f;
; #pragma unroll
;                 for (int bj = 0; bj < 2; ++bj) {
;                     float xo[8]; unpack8(xold[m][bj], xo);
;                     f32x4 v0 = acc[ai][bj][m][0] * rsf * g4[bj][0], v1 = acc[ai][bj][m][1] * rsf * g4[bj][1];
;                     float xn[8];
; #pragma unroll
;                     for (int e = 0; e < 4; ++e) { xn[e] = xo[e] + v0[e]; xn[4 + e] = xo[4 + e] + v1[e]; }
;                     if (outf) { *(f32x4*)(outf + off + bj * 128) = (f32x4){xn[0], xn[1], xn[2], xn[3]}; *(f32x4*)(outf + off + bj * 128 + 4) = (f32x4){xn[4], xn[5], xn[6], xn[7]}; }
;                     else { *(uint4*)(XB + off + bj * 128) = pack8(xn); }
; #pragma unroll
;                     for (int e = 0; e < 8; ++e) q += xn[e] * xn[e];
;                 }
;                 q += __shfl_xor(q, 16); q += __shfl_xor(q, 32);
;                 if (fq == 0) P[rl * 4 + wc] = q;
.LBB0_615:
	v_pk_mul_f32 v[58:59], v[58:59], v[58:59]
	v_pk_mul_f32 v[60:61], v[60:61], v[60:61]
	v_add_f32_e32 v5, v58, v59
	v_add_f32_e32 v5, v60, v5
	v_pk_mul_f32 v[54:55], v[54:55], v[54:55]
	v_add_f32_e32 v5, v61, v5
	v_add_f32_e32 v5, v54, v5
	v_pk_mul_f32 v[56:57], v[56:57], v[56:57]
	v_add_f32_e32 v5, v55, v5
	v_add_f32_e32 v5, v56, v5
	v_pk_mul_f32 v[50:51], v[50:51], v[50:51]
	v_add_f32_e32 v5, v57, v5
	v_add_f32_e32 v5, v50, v5
	v_pk_mul_f32 v[52:53], v[52:53], v[52:53]
	v_add_f32_e32 v5, v51, v5
	v_add_f32_e32 v5, v52, v5
	v_pk_mul_f32 v[62:63], v[62:63], v[62:63]
	v_add_f32_e32 v5, v53, v5
	v_add_f32_e32 v5, v62, v5
	v_pk_mul_f32 v[64:65], v[64:65], v[64:65]
	v_add_f32_e32 v5, v63, v5
	v_add_f32_e32 v5, v64, v5
	v_add_f32_e32 v5, v65, v5
	v_mov_b32_e32 v50, v5
	s_waitcnt lgkmcnt(0)
	s_nop 0
	v_permlane16_swap_b32 v50, v5
	v_add_f32_e32 v5, v5, v50
	v_mov_b32_e32 v50, v5
	s_nop 1
	v_permlane32_swap_b32 v50, v5
	s_and_saveexec_b64 s[82:83], s[4:5]
	s_cbranch_execz .LBB0_617
	s_waitcnt lgkmcnt(0)
	v_add_f32_e32 v5, v5, v50
	ds_write_b32 v238, v5

; __device__ __forceinline__ uint4 pack8(const float* f) { uint4 o; o.x = pk2(f[0], f[1]); o.y = pk2(f[2], f[3]); o.z = pk2(f[4], f[5]); o.w = pk2(f[6], f[7]); return o; }
;     __device__ __forceinline__ void fused(f32x4 (&acc)[2][2][4][2], const pg8::Unit& u, int wr, int wc, int fr, int fq, LAS unsigned char* lds, int wid, int lane) const {
;     ...
;             for (int m = 0; m < 4; ++m) {
;                 const int rl = ai * 128 + wr * 64 + m * 16 + fr; const size_t off = (size_t)(u.pm * 256 + rl) * 1024 + cb;
;                 const float rsf = S[rl]; float q = 0.f;
; #pragma unroll
;                 for (int bj = 0; bj < 2; ++bj) {
;                     float xo[8]; unpack8(xold[m][bj], xo);
;                     f32x4 v0 = acc[ai][bj][m][0] * rsf * g4[bj][0], v1 = acc[ai][bj][m][1] * rsf * g4[bj][1];
;                     float xn[8];
; #pragma unroll
;                     for (int e = 0; e < 4; ++e) { xn[e] = xo[e] + v0[e]; xn[4 + e] = xo[4 + e] + v1[e]; }
;                     if (outf) { *(f32x4*)(outf + off + bj * 128) = (f32x4){xn[0], xn[1], xn[2], xn[3]}; *(f32x4*)(outf + off + bj * 128 + 4) = (f32x4){xn[4], xn[5], xn[6], xn[7]}; }
;                     else { *(uint4*)(XB + off + bj * 128) = pack8(xn); }
; #pragma unroll
;                     for (int e = 0; e < 8; ++e) q += xn[e] * xn[e];
;                 }
;                 q += __shfl_xor(q, 16); q += __shfl_xor(q, 32);
;                 if (fq == 0) P[rl * 4 + wc] = q;
.LBB0_625:
	v_pk_mul_f32 v[46:47], v[46:47], v[46:47]
	v_pk_mul_f32 v[48:49], v[48:49], v[48:49]
	v_add_f32_e32 v5, v46, v47
	v_add_f32_e32 v5, v48, v5
	v_pk_mul_f32 v[50:51], v[50:51], v[50:51]
	v_add_f32_e32 v5, v49, v5
	v_add_f32_e32 v5, v50, v5
	v_pk_mul_f32 v[52:53], v[52:53], v[52:53]
	v_add_f32_e32 v5, v51, v5
	v_add_f32_e32 v5, v52, v5
	v_pk_mul_f32 v[42:43], v[42:43], v[42:43]
	v_add_f32_e32 v5, v53, v5
	v_add_f32_e32 v5, v42, v5
	v_pk_mul_f32 v[44:45], v[44:45], v[44:45]
	v_add_f32_e32 v5, v43, v5
	v_add_f32_e32 v5, v44, v5
	v_pk_mul_f32 v[54:55], v[54:55], v[54:55]
	v_add_f32_e32 v5, v45, v5
	v_add_f32_e32 v5, v54, v5
	v_pk_mul_f32 v[56:57], v[56:57], v[56:57]
	v_add_f32_e32 v5, v55, v5
	v_add_f32_e32 v5, v56, v5
	v_add_f32_e32 v5, v57, v5
	v_mov_b32_e32 v42, v5
	s_waitcnt lgkmcnt(0)
	s_nop 0
	v_permlane16_swap_b32 v42, v5
	v_add_f32_e32 v5, v5, v42
	v_mov_b32_e32 v42, v5
	s_nop 1
	v_permlane32_swap_b32 v42, v5
	s_and_saveexec_b64 s[82:83], s[4:5]
	s_cbranch_execz .LBB0_627
	s_waitcnt lgkmcnt(0)
	v_add_f32_e32 v5, v5, v42
	ds_write_b32 v236, v5

; __device__ __forceinline__ uint4 pack8(const float* f) { uint4 o; o.x = pk2(f[0], f[1]); o.y = pk2(f[2], f[3]); o.z = pk2(f[4], f[5]); o.w = pk2(f[6], f[7]); return o; }
;     __device__ __forceinline__ void fused(f32x4 (&acc)[2][2][4][2], const pg8::Unit& u, int wr, int wc, int fr, int fq, LAS unsigned char* lds, int wid, int lane) const {
;     ...
;             for (int m = 0; m < 4; ++m) {
;                 const int rl = ai * 128 + wr * 64 + m * 16 + fr; const size_t off = (size_t)(u.pm * 256 + rl) * 1024 + cb;
;                 const float rsf = S[rl]; float q = 0.f;
; #pragma unroll
;                 for (int bj = 0; bj < 2; ++bj) {
;                     float xo[8]; unpack8(xold[m][bj], xo);
;                     f32x4 v0 = acc[ai][bj][m][0] * rsf * g4[bj][0], v1 = acc[ai][bj][m][1] * rsf * g4[bj][1];
;                     float xn[8];
; #pragma unroll
;                     for (int e = 0; e < 4; ++e) { xn[e] = xo[e] + v0[e]; xn[4 + e] = xo[4 + e] + v1[e]; }
;                     if (outf) { *(f32x4*)(outf + off + bj * 128) = (f32x4){xn[0], xn[1], xn[2], xn[3]}; *(f32x4*)(outf + off + bj * 128 + 4) = (f32x4){xn[4], xn[5], xn[6], xn[7]}; }
;                     else { *(uint4*)(XB + off + bj * 128) = pack8(xn); }
; #pragma unroll
;                     for (int e = 0; e < 8; ++e) q += xn[e] * xn[e];
;                 }
;                 q += __shfl_xor(q, 16); q += __shfl_xor(q, 32);
;                 if (fq == 0) P[rl * 4 + wc] = q;
.LBB0_635:
	v_pk_mul_f32 v[38:39], v[38:39], v[38:39]
	v_pk_mul_f32 v[40:41], v[40:41], v[40:41]
	v_add_f32_e32 v5, v38, v39
	v_add_f32_e32 v5, v40, v5
	v_pk_mul_f32 v[42:43], v[42:43], v[42:43]
	v_add_f32_e32 v5, v41, v5
	v_add_f32_e32 v5, v42, v5
	v_pk_mul_f32 v[44:45], v[44:45], v[44:45]
	v_add_f32_e32 v5, v43, v5
	v_add_f32_e32 v5, v44, v5
	v_pk_mul_f32 v[34:35], v[34:35], v[34:35]
	v_add_f32_e32 v5, v45, v5
	v_add_f32_e32 v5, v34, v5
	v_pk_mul_f32 v[36:37], v[36:37], v[36:37]
	v_add_f32_e32 v5, v35, v5
	v_add_f32_e32 v5, v36, v5
	v_pk_mul_f32 v[46:47], v[46:47], v[46:47]
	v_add_f32_e32 v5, v37, v5
	v_add_f32_e32 v5, v46, v5
	v_pk_mul_f32 v[48:49], v[48:49], v[48:49]
	v_add_f32_e32 v5, v47, v5
	v_add_f32_e32 v5, v48, v5
	v_add_f32_e32 v5, v49, v5
	v_mov_b32_e32 v34, v5
	s_waitcnt lgkmcnt(0)
	s_nop 0
	v_permlane16_swap_b32 v34, v5
	v_add_f32_e32 v5, v5, v34
	v_mov_b32_e32 v34, v5
	s_nop 1
	v_permlane32_swap_b32 v34, v5
	s_and_saveexec_b64 s[82:83], s[4:5]
	s_cbranch_execz .LBB0_637
	s_waitcnt lgkmcnt(0)
	v_add_f32_e32 v5, v5, v34
	ds_write_b32 v234, v5

; __device__ __forceinline__ uint4 pack8(const float* f) { uint4 o; o.x = pk2(f[0], f[1]); o.y = pk2(f[2], f[3]); o.z = pk2(f[4], f[5]); o.w = pk2(f[6], f[7]); return o; }
;     __device__ __forceinline__ void fused(f32x4 (&acc)[2][2][4][2], const pg8::Unit& u, int wr, int wc, int fr, int fq, LAS unsigned char* lds, int wid, int lane) const {
;     ...
;             for (int m = 0; m < 4; ++m) {
;                 const int rl = ai * 128 + wr * 64 + m * 16 + fr; const size_t off = (size_t)(u.pm * 256 + rl) * 1024 + cb;
;                 const float rsf = S[rl]; float q = 0.f;
; #pragma unroll
;                 for (int bj = 0; bj < 2; ++bj) {
;                     float xo[8]; unpack8(xold[m][bj], xo);
;                     f32x4 v0 = acc[ai][bj][m][0] * rsf * g4[bj][0], v1 = acc[ai][bj][m][1] * rsf * g4[bj][1];
;                     float xn[8];
; #pragma unroll
;                     for (int e = 0; e < 4; ++e) { xn[e] = xo[e] + v0[e]; xn[4 + e] = xo[4 + e] + v1[e]; }
;                     if (outf) { *(f32x4*)(outf + off + bj * 128) = (f32x4){xn[0], xn[1], xn[2], xn[3]}; *(f32x4*)(outf + off + bj * 128 + 4) = (f32x4){xn[4], xn[5], xn[6], xn[7]}; }
;                     else { *(uint4*)(XB + off + bj * 128) = pack8(xn); }
; #pragma unroll
;                     for (int e = 0; e < 8; ++e) q += xn[e] * xn[e];
;                 }
;                 q += __shfl_xor(q, 16); q += __shfl_xor(q, 32);
;                 if (fq == 0) P[rl * 4 + wc] = q;
.LBB0_645:
	v_pk_mul_f32 v[30:31], v[30:31], v[30:31]
	v_pk_mul_f32 v[32:33], v[32:33], v[32:33]
	v_add_f32_e32 v5, v30, v31
	v_add_f32_e32 v5, v32, v5
	v_pk_mul_f32 v[34:35], v[34:35], v[34:35]
	v_add_f32_e32 v5, v33, v5
	v_add_f32_e32 v5, v34, v5
	v_pk_mul_f32 v[36:37], v[36:37], v[36:37]
	v_add_f32_e32 v5, v35, v5
	v_add_f32_e32 v5, v36, v5
	v_pk_mul_f32 v[26:27], v[26:27], v[26:27]
	v_add_f32_e32 v5, v37, v5
	v_add_f32_e32 v5, v26, v5
	v_pk_mul_f32 v[28:29], v[28:29], v[28:29]
	v_add_f32_e32 v5, v27, v5
	v_add_f32_e32 v5, v28, v5
	v_pk_mul_f32 v[38:39], v[38:39], v[38:39]
	v_add_f32_e32 v5, v29, v5
	v_add_f32_e32 v5, v38, v5
	v_pk_mul_f32 v[40:41], v[40:41], v[40:41]
	v_add_f32_e32 v5, v39, v5
	v_add_f32_e32 v5, v40, v5
	v_add_f32_e32 v5, v41, v5
	v_mov_b32_e32 v26, v5
	s_waitcnt lgkmcnt(0)
	s_nop 0
	v_permlane16_swap_b32 v26, v5
	v_add_f32_e32 v5, v5, v26
	v_mov_b32_e32 v26, v5
	s_nop 1
	v_permlane32_swap_b32 v26, v5
	s_and_saveexec_b64 s[82:83], s[4:5]
	s_cbranch_execz .LBB0_647
	s_waitcnt lgkmcnt(0)
	v_add_f32_e32 v5, v5, v26
	ds_write_b32 v232, v5

; __device__ __forceinline__ uint4 pack8(const float* f) { uint4 o; o.x = pk2(f[0], f[1]); o.y = pk2(f[2], f[3]); o.z = pk2(f[4], f[5]); o.w = pk2(f[6], f[7]); return o; }
;     __device__ __forceinline__ void fused(f32x4 (&acc)[2][2][4][2], const pg8::Unit& u, int wr, int wc, int fr, int fq, LAS unsigned char* lds, int wid, int lane) const {
;     ...
;             for (int m = 0; m < 4; ++m) {
;                 const int rl = ai * 128 + wr * 64 + m * 16 + fr; const size_t off = (size_t)(u.pm * 256 + rl) * 1024 + cb;
;                 const float rsf = S[rl]; float q = 0.f;
; #pragma unroll
;                 for (int bj = 0; bj < 2; ++bj) {
;                     float xo[8]; unpack8(xold[m][bj], xo);
;                     f32x4 v0 = acc[ai][bj][m][0] * rsf * g4[bj][0], v1 = acc[ai][bj][m][1] * rsf * g4[bj][1];
;                     float xn[8];
; #pragma unroll
;                     for (int e = 0; e < 4; ++e) { xn[e] = xo[e] + v0[e]; xn[4 + e] = xo[4 + e] + v1[e]; }
;                     if (outf) { *(f32x4*)(outf + off + bj * 128) = (f32x4){xn[0], xn[1], xn[2], xn[3]}; *(f32x4*)(outf + off + bj * 128 + 4) = (f32x4){xn[4], xn[5], xn[6], xn[7]}; }
;                     else { *(uint4*)(XB + off + bj * 128) = pack8(xn); }
; #pragma unroll
;                     for (int e = 0; e < 8; ++e) q += xn[e] * xn[e];
;                 }
;                 q += __shfl_xor(q, 16); q += __shfl_xor(q, 32);
;                 if (fq == 0) P[rl * 4 + wc] = q;
.LBB0_655:
	v_pk_mul_f32 v[58:59], v[58:59], v[58:59]
	v_pk_mul_f32 v[60:61], v[60:61], v[60:61]
	v_add_f32_e32 v5, v58, v59
	v_add_f32_e32 v5, v60, v5
	v_pk_mul_f32 v[54:55], v[54:55], v[54:55]
	v_add_f32_e32 v5, v61, v5
	v_add_f32_e32 v5, v54, v5
	v_pk_mul_f32 v[56:57], v[56:57], v[56:57]
	v_add_f32_e32 v5, v55, v5
	v_add_f32_e32 v5, v56, v5
	v_pk_mul_f32 v[50:51], v[50:51], v[50:51]
	v_add_f32_e32 v5, v57, v5
	v_add_f32_e32 v5, v50, v5
	v_pk_mul_f32 v[52:53], v[52:53], v[52:53]
	v_add_f32_e32 v5, v51, v5
	v_add_f32_e32 v5, v52, v5
	v_pk_mul_f32 v[62:63], v[62:63], v[62:63]
	v_add_f32_e32 v5, v53, v5
	v_add_f32_e32 v5, v62, v5
	v_pk_mul_f32 v[64:65], v[64:65], v[64:65]
	v_add_f32_e32 v5, v63, v5
	v_add_f32_e32 v5, v64, v5
	v_add_f32_e32 v5, v65, v5
	v_mov_b32_e32 v50, v5
	s_waitcnt lgkmcnt(0)
	s_nop 0
	v_permlane16_swap_b32 v50, v5
	v_add_f32_e32 v5, v5, v50
	v_mov_b32_e32 v50, v5
	s_nop 1
	v_permlane32_swap_b32 v50, v5
	s_and_saveexec_b64 s[82:83], s[4:5]
	s_cbranch_execz .LBB0_657
	s_waitcnt lgkmcnt(0)
	v_add_f32_e32 v5, v5, v50
	ds_write_b32 v230, v5

; __device__ __forceinline__ uint4 pack8(const float* f) { uint4 o; o.x = pk2(f[0], f[1]); o.y = pk2(f[2], f[3]); o.z = pk2(f[4], f[5]); o.w = pk2(f[6], f[7]); return o; }
;     __device__ __forceinline__ void fused(f32x4 (&acc)[2][2][4][2], const pg8::Unit& u, int wr, int wc, int fr, int fq, LAS unsigned char* lds, int wid, int lane) const {
;     ...
;             for (int m = 0; m < 4; ++m) {
;                 const int rl = ai * 128 + wr * 64 + m * 16 + fr; const size_t off = (size_t)(u.pm * 256 + rl) * 1024 + cb;
;                 const float rsf = S[rl]; float q = 0.f;
; #pragma unroll
;                 for (int bj = 0; bj < 2; ++bj) {
;                     float xo[8]; unpack8(xold[m][bj], xo);
;                     f32x4 v0 = acc[ai][bj][m][0] * rsf * g4[bj][0], v1 = acc[ai][bj][m][1] * rsf * g4[bj][1];
;                     float xn[8];
; #pragma unroll
;                     for (int e = 0; e < 4; ++e) { xn[e] = xo[e] + v0[e]; xn[4 + e] = xo[4 + e] + v1[e]; }
;                     if (outf) { *(f32x4*)(outf + off + bj * 128) = (f32x4){xn[0], xn[1], xn[2], xn[3]}; *(f32x4*)(outf + off + bj * 128 + 4) = (f32x4){xn[4], xn[5], xn[6], xn[7]}; }
;                     else { *(uint4*)(XB + off + bj * 128) = pack8(xn); }
; #pragma unroll
;                     for (int e = 0; e < 8; ++e) q += xn[e] * xn[e];
;                 }
;                 q += __shfl_xor(q, 16); q += __shfl_xor(q, 32);
;                 if (fq == 0) P[rl * 4 + wc] = q;
.LBB0_665:
	v_pk_mul_f32 v[46:47], v[46:47], v[46:47]
	v_pk_mul_f32 v[48:49], v[48:49], v[48:49]
	v_add_f32_e32 v5, v46, v47
	v_add_f32_e32 v5, v48, v5
	v_pk_mul_f32 v[50:51], v[50:51], v[50:51]
	v_add_f32_e32 v5, v49, v5
	v_add_f32_e32 v5, v50, v5
	v_pk_mul_f32 v[52:53], v[52:53], v[52:53]
	v_add_f32_e32 v5, v51, v5
	v_add_f32_e32 v5, v52, v5
	v_pk_mul_f32 v[42:43], v[42:43], v[42:43]
	v_add_f32_e32 v5, v53, v5
	v_add_f32_e32 v5, v42, v5
	v_pk_mul_f32 v[44:45], v[44:45], v[44:45]
	v_add_f32_e32 v5, v43, v5
	v_add_f32_e32 v5, v44, v5
	v_pk_mul_f32 v[54:55], v[54:55], v[54:55]
	v_add_f32_e32 v5, v45, v5
	v_add_f32_e32 v5, v54, v5
	v_pk_mul_f32 v[56:57], v[56:57], v[56:57]
	v_add_f32_e32 v5, v55, v5
	v_add_f32_e32 v5, v56, v5
	v_add_f32_e32 v5, v57, v5
	v_mov_b32_e32 v42, v5
	s_waitcnt lgkmcnt(0)
	s_nop 0
	v_permlane16_swap_b32 v42, v5
	v_add_f32_e32 v5, v5, v42
	v_mov_b32_e32 v42, v5
	s_nop 1
	v_permlane32_swap_b32 v42, v5
	s_and_saveexec_b64 s[82:83], s[4:5]
	s_cbranch_execz .LBB0_667
	s_waitcnt lgkmcnt(0)
	v_add_f32_e32 v5, v5, v42
	ds_write_b32 v228, v5

; __device__ __forceinline__ uint4 pack8(const float* f) { uint4 o; o.x = pk2(f[0], f[1]); o.y = pk2(f[2], f[3]); o.z = pk2(f[4], f[5]); o.w = pk2(f[6], f[7]); return o; }
;     __device__ __forceinline__ void fused(f32x4 (&acc)[2][2][4][2], const pg8::Unit& u, int wr, int wc, int fr, int fq, LAS unsigned char* lds, int wid, int lane) const {
;     ...
;             for (int m = 0; m < 4; ++m) {
;                 const int rl = ai * 128 + wr * 64 + m * 16 + fr; const size_t off = (size_t)(u.pm * 256 + rl) * 1024 + cb;
;                 const float rsf = S[rl]; float q = 0.f;
; #pragma unroll
;                 for (int bj = 0; bj < 2; ++bj) {
;                     float xo[8]; unpack8(xold[m][bj], xo);
;                     f32x4 v0 = acc[ai][bj][m][0] * rsf * g4[bj][0], v1 = acc[ai][bj][m][1] * rsf * g4[bj][1];
;                     float xn[8];
; #pragma unroll
;                     for (int e = 0; e < 4; ++e) { xn[e] = xo[e] + v0[e]; xn[4 + e] = xo[4 + e] + v1[e]; }
;                     if (outf) { *(f32x4*)(outf + off + bj * 128) = (f32x4){xn[0], xn[1], xn[2], xn[3]}; *(f32x4*)(outf + off + bj * 128 + 4) = (f32x4){xn[4], xn[5], xn[6], xn[7]}; }
;                     else { *(uint4*)(XB + off + bj * 128) = pack8(xn); }
; #pragma unroll
;                     for (int e = 0; e < 8; ++e) q += xn[e] * xn[e];
;                 }
;                 q += __shfl_xor(q, 16); q += __shfl_xor(q, 32);
;                 if (fq == 0) P[rl * 4 + wc] = q;
.LBB0_675:
	v_pk_mul_f32 v[38:39], v[38:39], v[38:39]
	v_pk_mul_f32 v[40:41], v[40:41], v[40:41]
	v_add_f32_e32 v5, v38, v39
	v_add_f32_e32 v5, v40, v5
	v_pk_mul_f32 v[42:43], v[42:43], v[42:43]
	v_add_f32_e32 v5, v41, v5
	v_add_f32_e32 v5, v42, v5
	v_pk_mul_f32 v[44:45], v[44:45], v[44:45]
	v_add_f32_e32 v5, v43, v5
	v_add_f32_e32 v5, v44, v5
	v_pk_mul_f32 v[34:35], v[34:35], v[34:35]
	v_add_f32_e32 v5, v45, v5
	v_add_f32_e32 v5, v34, v5
	v_pk_mul_f32 v[36:37], v[36:37], v[36:37]
	v_add_f32_e32 v5, v35, v5
	v_add_f32_e32 v5, v36, v5
	v_pk_mul_f32 v[46:47], v[46:47], v[46:47]
	v_add_f32_e32 v5, v37, v5
	v_add_f32_e32 v5, v46, v5
	v_pk_mul_f32 v[48:49], v[48:49], v[48:49]
	v_add_f32_e32 v5, v47, v5
	v_add_f32_e32 v5, v48, v5
	v_add_f32_e32 v5, v49, v5
	v_mov_b32_e32 v34, v5
	s_waitcnt lgkmcnt(0)
	s_nop 0
	v_permlane16_swap_b32 v34, v5
	v_add_f32_e32 v5, v5, v34
	v_mov_b32_e32 v34, v5
	s_nop 1
	v_permlane32_swap_b32 v34, v5
	s_and_saveexec_b64 s[82:83], s[4:5]
	s_cbranch_execz .LBB0_677
	s_waitcnt lgkmcnt(0)
	v_add_f32_e32 v5, v5, v34
	ds_write_b32 v226, v5

; __device__ __forceinline__ uint4 pack8(const float* f) { uint4 o; o.x = pk2(f[0], f[1]); o.y = pk2(f[2], f[3]); o.z = pk2(f[4], f[5]); o.w = pk2(f[6], f[7]); return o; }
;     __device__ __forceinline__ void fused(f32x4 (&acc)[2][2][4][2], const pg8::Unit& u, int wr, int wc, int fr, int fq, LAS unsigned char* lds, int wid, int lane) const {
;     ...
;             for (int m = 0; m < 4; ++m) {
;                 const int rl = ai * 128 + wr * 64 + m * 16 + fr; const size_t off = (size_t)(u.pm * 256 + rl) * 1024 + cb;
;                 const float rsf = S[rl]; float q = 0.f;
; #pragma unroll
;                 for (int bj = 0; bj < 2; ++bj) {
;                     float xo[8]; unpack8(xold[m][bj], xo);
;                     f32x4 v0 = acc[ai][bj][m][0] * rsf * g4[bj][0], v1 = acc[ai][bj][m][1] * rsf * g4[bj][1];
;                     float xn[8];
; #pragma unroll
;                     for (int e = 0; e < 4; ++e) { xn[e] = xo[e] + v0[e]; xn[4 + e] = xo[4 + e] + v1[e]; }
;                     if (outf) { *(f32x4*)(outf + off + bj * 128) = (f32x4){xn[0], xn[1], xn[2], xn[3]}; *(f32x4*)(outf + off + bj * 128 + 4) = (f32x4){xn[4], xn[5], xn[6], xn[7]}; }
;                     else { *(uint4*)(XB + off + bj * 128) = pack8(xn); }
; #pragma unroll
;                     for (int e = 0; e < 8; ++e) q += xn[e] * xn[e];
;                 }
;                 q += __shfl_xor(q, 16); q += __shfl_xor(q, 32);
;                 if (fq == 0) P[rl * 4 + wc] = q;
.LBB0_685:
	v_pk_mul_f32 v[22:23], v[22:23], v[22:23]
	v_pk_mul_f32 v[24:25], v[24:25], v[24:25]
	v_add_f32_e32 v5, v22, v23
	v_add_f32_e32 v5, v24, v5
	v_pk_mul_f32 v[18:19], v[18:19], v[18:19]
	v_add_f32_e32 v5, v25, v5
	v_add_f32_e32 v5, v18, v5
	v_pk_mul_f32 v[20:21], v[20:21], v[20:21]
	v_add_f32_e32 v5, v19, v5
	v_add_f32_e32 v5, v20, v5
	v_pk_mul_f32 v[14:15], v[14:15], v[14:15]
	v_add_f32_e32 v5, v21, v5
	v_add_f32_e32 v5, v14, v5
	v_pk_mul_f32 v[16:17], v[16:17], v[16:17]
	v_add_f32_e32 v5, v15, v5
	v_add_f32_e32 v5, v16, v5
	v_pk_mul_f32 v[10:11], v[10:11], v[10:11]
	v_add_f32_e32 v5, v17, v5
	v_add_f32_e32 v5, v10, v5
	v_pk_mul_f32 v[12:13], v[12:13], v[12:13]
	v_add_f32_e32 v5, v11, v5
	v_add_f32_e32 v5, v12, v5
	v_add_f32_e32 v5, v13, v5
	v_mov_b32_e32 v10, v5
	s_waitcnt lgkmcnt(0)
	s_nop 0
	v_permlane16_swap_b32 v10, v5
	v_add_f32_e32 v5, v5, v10
	v_mov_b32_e32 v10, v5
	s_nop 1
	v_permlane32_swap_b32 v10, v5
	s_and_saveexec_b64 s[8:9], s[4:5]
	s_cbranch_execz .LBB0_687
	s_waitcnt lgkmcnt(0)
	v_add_f32_e32 v5, v5, v10
	ds_write_b32 v2, v5
